# F13 + fmix stage-V staging: the unit's eight row loads issued together, LDS scatter writes behind counted waits (one round trip instead of eight)
# speedup vs baseline: 1.0083x; 1.0022x over previous
.LBB1_480:
	s_ashr_i32 s1, s26, 7
	s_and_b32 s5, s27, 0x1fc
	s_lshl_b32 s6, s1, 9
	s_or_b32 s16, s6, s5
	s_ashr_i32 s17, s16, 31
	s_lshl_b64 s[6:7], s[16:17], 14
	s_add_u32 s6, s10, s6
	s_addc_u32 s7, s11, s7
	v_lshl_add_u64 v[0:1], s[6:7], 0, v[112:113]
	v_lshl_add_u64 v[4:5], v[0:1], 0, s[38:39]
	s_waitcnt vmcnt(0) lgkmcnt(0)
	s_barrier
	global_load_dwordx4 v[172:175], v[4:5], off
	v_add_co_u32_e32 v0, vcc, s75, v4
	s_nop 1
	v_addc_co_u32_e32 v1, vcc, 0, v5, vcc
	global_load_dwordx4 v[8:11], v[0:1], off
	s_or_b32 s6, s16, 1
	s_ashr_i32 s7, s6, 31
	s_lshl_b64 s[6:7], s[6:7], 14
	s_add_u32 s6, s10, s6
	s_addc_u32 s7, s11, s7
	v_lshl_add_u64 v[0:1], s[6:7], 0, v[112:113]
	v_lshl_add_u64 v[4:5], v[0:1], 0, s[38:39]
	global_load_dwordx4 v[12:15], v[4:5], off
	v_add_co_u32_e32 v0, vcc, s75, v4
	s_nop 1
	v_addc_co_u32_e32 v1, vcc, 0, v5, vcc
	global_load_dwordx4 v[18:21], v[0:1], off
	s_or_b32 s6, s16, 2
	s_ashr_i32 s7, s6, 31
	s_lshl_b64 s[6:7], s[6:7], 14
	s_add_u32 s6, s10, s6
	s_addc_u32 s7, s11, s7
	v_lshl_add_u64 v[0:1], s[6:7], 0, v[112:113]
	v_lshl_add_u64 v[4:5], v[0:1], 0, s[38:39]
	global_load_dwordx4 v[22:25], v[4:5], off
	v_add_co_u32_e32 v0, vcc, s75, v4
	s_nop 1
	v_addc_co_u32_e32 v1, vcc, 0, v5, vcc
	global_load_dwordx4 v[26:29], v[0:1], off
	s_or_b32 s6, s16, 3
	s_ashr_i32 s7, s6, 31
	s_lshl_b64 s[6:7], s[6:7], 14
	s_add_u32 s6, s10, s6
	s_addc_u32 s7, s11, s7
	v_lshl_add_u64 v[0:1], s[6:7], 0, v[112:113]
	v_lshl_add_u64 v[4:5], v[0:1], 0, s[38:39]
	global_load_dwordx4 v[30:33], v[4:5], off
	v_add_co_u32_e32 v0, vcc, s75, v4
	s_nop 1
	v_addc_co_u32_e32 v1, vcc, 0, v5, vcc
	global_load_dwordx4 v[168:171], v[0:1], off
	s_lshl_b32 s1, s1, 12
	s_lshl_b32 s5, s5, 1
	s_add_u32 s16, s24, s5
	s_addc_u32 s17, s25, 0
	s_add_i32 s26, s26, s33
	s_add_i32 s27, s27, s9
	s_cmpk_lt_i32 s26, 0x100
	v_add_u32_e32 v6, s18, v131
	v_add_u32_e32 v16, v132, v134
	v_add_u32_e32 v17, v133, v135
	s_waitcnt vmcnt(7)
	ds_write_b16 v6, v172 offset:55296
	ds_write_b16_d16_hi v6, v172 offset:55584
	ds_write_b16 v6, v173 offset:55872
	ds_write_b16_d16_hi v6, v173 offset:56160
	ds_write_b16 v6, v174 offset:56448
	ds_write_b16_d16_hi v6, v174 offset:56736
	ds_write_b16 v6, v175 offset:57024
	ds_write_b16_d16_hi v6, v175 offset:57312
	s_waitcnt vmcnt(6)
	ds_write_b16 v6, v8 offset:55424
	ds_write_b16_d16_hi v6, v8 offset:55712
	ds_write_b16 v6, v9 offset:56000
	ds_write_b16_d16_hi v6, v9 offset:56288
	ds_write_b16 v6, v10 offset:56576
	ds_write_b16_d16_hi v6, v10 offset:56864
	ds_write_b16 v6, v11 offset:57152
	ds_write_b16_d16_hi v6, v11 offset:57440
	v_add_u32_e32 v6, s19, v131
	s_waitcnt vmcnt(5)
	ds_write_b16 v6, v12 offset:18432
	ds_write_b16_d16_hi v6, v12 offset:18720
	ds_write_b16 v6, v13 offset:19008
	ds_write_b16_d16_hi v6, v13 offset:19296
	ds_write_b16 v6, v14 offset:19584
	ds_write_b16_d16_hi v6, v14 offset:19872
	ds_write_b16 v6, v15 offset:20160
	ds_write_b16_d16_hi v6, v15 offset:20448
	s_waitcnt vmcnt(4)
	ds_write_b16 v6, v18 offset:18560
	ds_write_b16_d16_hi v6, v18 offset:18848
	ds_write_b16 v6, v19 offset:19136
	ds_write_b16_d16_hi v6, v19 offset:19424
	ds_write_b16 v6, v20 offset:19712
	ds_write_b16_d16_hi v6, v20 offset:20000
	ds_write_b16 v6, v21 offset:20288
	ds_write_b16_d16_hi v6, v21 offset:20576
	s_waitcnt vmcnt(3)
	ds_write_b16 v6, v22 offset:36864
	ds_write_b16_d16_hi v6, v22 offset:37152
	ds_write_b16 v6, v23 offset:37440
	ds_write_b16_d16_hi v6, v23 offset:37728
	ds_write_b16 v6, v24 offset:38016
	ds_write_b16_d16_hi v6, v24 offset:38304
	ds_write_b16 v6, v25 offset:38592
	ds_write_b16_d16_hi v6, v25 offset:38880
	s_waitcnt vmcnt(2)
	ds_write_b16 v6, v26 offset:36992
	ds_write_b16_d16_hi v6, v26 offset:37280
	ds_write_b16 v6, v27 offset:37568
	ds_write_b16_d16_hi v6, v27 offset:37856
	ds_write_b16 v6, v28 offset:38144
	ds_write_b16_d16_hi v6, v28 offset:38432
	ds_write_b16 v6, v29 offset:38720
	ds_write_b16_d16_hi v6, v29 offset:39008
	s_waitcnt vmcnt(1)
	ds_write_b16 v6, v30 offset:55296
	ds_write_b16_d16_hi v6, v30 offset:55584
	ds_write_b16 v6, v31 offset:55872
	ds_write_b16_d16_hi v6, v31 offset:56160
	ds_write_b16 v6, v32 offset:56448
	ds_write_b16_d16_hi v6, v32 offset:56736
	ds_write_b16 v6, v33 offset:57024
	ds_write_b16_d16_hi v6, v33 offset:57312
	s_waitcnt vmcnt(0)
	ds_write_b16 v6, v168 offset:55424
	ds_write_b16_d16_hi v6, v168 offset:55712
	ds_write_b16 v6, v169 offset:56000
	ds_write_b16_d16_hi v6, v169 offset:56288
	ds_write_b16 v6, v170 offset:56576
	ds_write_b16_d16_hi v6, v170 offset:56864
	ds_write_b16 v6, v171 offset:57152
	ds_write_b16_d16_hi v6, v171 offset:57440
	s_waitcnt lgkmcnt(0)
	s_barrier
	ds_read_b128 v[12:15], v16
	ds_read_b128 v[8:11], v16 offset:4608
	ds_read_b128 v[4:7], v16 offset:18432
	ds_read_b128 v[0:3], v16 offset:23040
	ds_read_b128 v[18:21], v17 offset:55296
	ds_read_b128 v[22:25], v17 offset:59904
	ds_read_b128 v[26:29], v17 offset:64512
	ds_read_b128 v[30:33], v151 offset:64512
	s_waitcnt lgkmcnt(3)
	v_mfma_f32_16x16x32_bf16 v[34:37], v[12:15], v[18:21], 0
	s_waitcnt lgkmcnt(2)
	v_mfma_f32_16x16x32_bf16 v[38:41], v[12:15], v[22:25], 0
	s_waitcnt lgkmcnt(1)
	v_mfma_f32_16x16x32_bf16 v[42:45], v[12:15], v[26:29], 0
	s_waitcnt lgkmcnt(0)
	v_mfma_f32_16x16x32_bf16 v[12:15], v[12:15], v[30:33], 0
	v_mfma_f32_16x16x32_bf16 v[46:49], v[8:11], v[18:21], 0
	v_mfma_f32_16x16x32_bf16 v[50:53], v[8:11], v[22:25], 0
	v_mfma_f32_16x16x32_bf16 v[54:57], v[8:11], v[26:29], 0
	v_mfma_f32_16x16x32_bf16 v[8:11], v[8:11], v[30:33], 0
	v_mfma_f32_16x16x32_bf16 v[58:61], v[4:7], v[18:21], 0
	v_mfma_f32_16x16x32_bf16 v[160:163], v[4:7], v[22:25], 0
	v_mfma_f32_16x16x32_bf16 v[164:167], v[4:7], v[26:29], 0
	v_mfma_f32_16x16x32_bf16 v[4:7], v[4:7], v[30:33], 0
	v_mfma_f32_16x16x32_bf16 v[18:21], v[0:3], v[18:21], 0
	v_mfma_f32_16x16x32_bf16 v[22:25], v[0:3], v[22:25], 0
	v_mfma_f32_16x16x32_bf16 v[26:29], v[0:3], v[26:29], 0
	v_mfma_f32_16x16x32_bf16 v[0:3], v[0:3], v[30:33], 0
	ds_read_b128 v[30:33], v16 offset:64
	ds_read_b128 v[168:171], v16 offset:4672
	ds_read_b128 v[172:175], v16 offset:18496
	ds_read_b128 v[176:179], v16 offset:23104
	ds_read_b128 v[180:183], v17 offset:55360
	ds_read_b128 v[184:187], v17 offset:59968
	ds_read_b128 v[188:191], v17 offset:64576
	ds_read_b128 v[206:209], v151 offset:64576
	s_waitcnt lgkmcnt(3)
	v_mfma_f32_16x16x32_bf16 v[34:37], v[30:33], v[180:183], v[34:37]
	s_waitcnt lgkmcnt(2)
	v_mfma_f32_16x16x32_bf16 v[38:41], v[30:33], v[184:187], v[38:41]
	s_waitcnt lgkmcnt(1)
	v_mfma_f32_16x16x32_bf16 v[42:45], v[30:33], v[188:191], v[42:45]
	s_waitcnt lgkmcnt(0)
	v_mfma_f32_16x16x32_bf16 v[12:15], v[30:33], v[206:209], v[12:15]
	v_mfma_f32_16x16x32_bf16 v[30:33], v[168:171], v[180:183], v[46:49]
	v_mfma_f32_16x16x32_bf16 v[46:49], v[168:171], v[184:187], v[50:53]
	v_mfma_f32_16x16x32_bf16 v[50:53], v[168:171], v[188:191], v[54:57]
	v_mfma_f32_16x16x32_bf16 v[8:11], v[168:171], v[206:209], v[8:11]
	v_mfma_f32_16x16x32_bf16 v[54:57], v[172:175], v[180:183], v[58:61]
	v_mfma_f32_16x16x32_bf16 v[58:61], v[172:175], v[184:187], v[160:163]
	v_mfma_f32_16x16x32_bf16 v[160:163], v[172:175], v[188:191], v[164:167]
	v_mfma_f32_16x16x32_bf16 v[4:7], v[172:175], v[206:209], v[4:7]
	v_mfma_f32_16x16x32_bf16 v[18:21], v[176:179], v[180:183], v[18:21]
	v_mfma_f32_16x16x32_bf16 v[22:25], v[176:179], v[184:187], v[22:25]
	v_mfma_f32_16x16x32_bf16 v[26:29], v[176:179], v[188:191], v[26:29]
	v_mfma_f32_16x16x32_bf16 v[0:3], v[176:179], v[206:209], v[0:3]
	ds_read_b128 v[164:167], v16 offset:128
	ds_read_b128 v[168:171], v16 offset:4736
	ds_read_b128 v[172:175], v16 offset:18560
	ds_read_b128 v[176:179], v16 offset:23168
	ds_read_b128 v[180:183], v17 offset:55424
	ds_read_b128 v[184:187], v17 offset:60032
	ds_read_b128 v[188:191], v17 offset:64640
	ds_read_b128 v[206:209], v151 offset:64640
	s_waitcnt lgkmcnt(3)
	v_mfma_f32_16x16x32_bf16 v[34:37], v[164:167], v[180:183], v[34:37]
	s_waitcnt lgkmcnt(2)
	v_mfma_f32_16x16x32_bf16 v[38:41], v[164:167], v[184:187], v[38:41]
	s_waitcnt lgkmcnt(1)
	v_mfma_f32_16x16x32_bf16 v[42:45], v[164:167], v[188:191], v[42:45]
	s_waitcnt lgkmcnt(0)
	v_mfma_f32_16x16x32_bf16 v[12:15], v[164:167], v[206:209], v[12:15]
	v_mfma_f32_16x16x32_bf16 v[164:167], v[168:171], v[180:183], v[30:33]
	v_mfma_f32_16x16x32_bf16 v[210:213], v[168:171], v[184:187], v[46:49]
	v_mfma_f32_16x16x32_bf16 v[234:237], v[168:171], v[188:191], v[50:53]
	v_mfma_f32_16x16x32_bf16 v[168:171], v[168:171], v[206:209], v[8:11]
	v_mfma_f32_16x16x32_bf16 v[52:55], v[172:175], v[180:183], v[54:57]
	v_mfma_f32_16x16x32_bf16 v[238:241], v[172:175], v[184:187], v[58:61]
	v_mfma_f32_16x16x32_bf16 v[160:163], v[172:175], v[188:191], v[160:163]
	v_mfma_f32_16x16x32_bf16 v[4:7], v[172:175], v[206:209], v[4:7]
	v_mfma_f32_16x16x32_bf16 v[172:175], v[176:179], v[180:183], v[18:21]
	v_mfma_f32_16x16x32_bf16 v[20:23], v[176:179], v[184:187], v[22:25]
	v_mfma_f32_16x16x32_bf16 v[180:183], v[176:179], v[188:191], v[26:29]
	v_mfma_f32_16x16x32_bf16 v[176:179], v[176:179], v[206:209], v[0:3]
	s_nop 2
	ds_read_b128 v[0:3], v16 offset:192
	ds_read_b128 v[28:31], v16 offset:4800
	ds_read_b128 v[184:187], v16 offset:18624
	ds_read_b128 v[188:191], v16 offset:23232
	ds_read_b128 v[206:209], v17 offset:55488
	ds_read_b128 v[242:245], v17 offset:60096
	ds_read_b128 v[246:249], v17 offset:64704
	ds_read_b128 v[198:201], v151 offset:64704
	s_waitcnt lgkmcnt(0)
	s_barrier
	v_mfma_f32_16x16x32_bf16 v[48:51], v[0:3], v[242:245], v[38:41]
	v_mfma_f32_16x16x32_bf16 v[40:43], v[0:3], v[246:249], v[42:45]
	v_mfma_f32_16x16x32_bf16 v[44:47], v[184:187], v[246:249], v[160:163]
	s_nop 2
	global_load_dwordx2 v[160:161], v[64:65], off
	v_mfma_f32_16x16x32_bf16 v[60:63], v[184:187], v[206:209], v[52:55]
	v_mfma_f32_16x16x32_bf16 v[56:59], v[0:3], v[206:209], v[34:37]
	v_mfma_f32_16x16x32_bf16 v[52:55], v[184:187], v[242:245], v[238:241]
	s_waitcnt vmcnt(0)
	s_nop 4
	v_mul_f32_e32 v162, v60, v161
	v_fmac_f32_e32 v162, v56, v160
	v_mul_f32_e32 v56, v56, v161
	v_fma_f32 v56, v60, v160, -v56
	global_load_dwordx2 v[160:161], v[66:67], off
	v_bfe_u32 v163, v162, 16, 1
	v_bfe_u32 v60, v56, 16, 1
	v_add3_u32 v162, v162, v163, s70
	v_add_u32_e32 v163, v136, v137
	v_add3_u32 v56, v56, v60, s70
	ds_write_b16_d16_hi v163, v56 offset:55424
	v_mfma_f32_16x16x32_bf16 v[36:39], v[184:187], v[198:201], v[4:7]
	ds_write_b16_d16_hi v163, v162 offset:55296
	s_waitcnt vmcnt(0)
	v_mul_f32_e32 v56, v61, v161
	v_fmac_f32_e32 v56, v57, v160
	v_bfe_u32 v60, v56, 16, 1
	v_add3_u32 v56, v56, v60, s70
	ds_write_b16_d16_hi v163, v56 offset:55584
	v_mul_f32_e32 v56, v57, v161
	v_fma_f32 v56, v61, v160, -v56
	v_bfe_u32 v57, v56, 16, 1
	v_add3_u32 v56, v56, v57, s70
	ds_write_b16_d16_hi v163, v56 offset:55712
	global_load_dwordx2 v[56:57], v[68:69], off
	v_mfma_f32_16x16x32_bf16 v[32:35], v[0:3], v[198:201], v[12:15]
	s_waitcnt vmcnt(0)
	v_mul_f32_e32 v60, v62, v57
	v_mul_f32_e32 v57, v58, v57
	v_fmac_f32_e32 v60, v58, v56
	v_fma_f32 v56, v62, v56, -v57
	v_bfe_u32 v57, v56, 16, 1
	v_add3_u32 v56, v56, v57, s70
	ds_write_b16_d16_hi v163, v56 offset:56000
	global_load_dwordx2 v[56:57], v[70:71], off
	v_bfe_u32 v61, v60, 16, 1
	v_add3_u32 v60, v60, v61, s70
	ds_write_b16_d16_hi v163, v60 offset:55872
	v_mfma_f32_16x16x32_bf16 v[24:27], v[28:31], v[206:209], v[164:167]
	s_waitcnt vmcnt(0)
	v_mul_f32_e32 v58, v63, v57
	v_mul_f32_e32 v57, v59, v57
	v_fmac_f32_e32 v58, v59, v56
	v_fma_f32 v56, v63, v56, -v57
	v_bfe_u32 v57, v56, 16, 1
	v_add3_u32 v56, v56, v57, s70
	ds_write_b16_d16_hi v163, v56 offset:56288
	global_load_dwordx2 v[56:57], v[72:73], off
	v_bfe_u32 v60, v58, 16, 1
	v_add3_u32 v58, v58, v60, s70
	ds_write_b16_d16_hi v163, v58 offset:56160
	v_mfma_f32_16x16x32_bf16 v[16:19], v[28:31], v[242:245], v[210:213]
	s_waitcnt vmcnt(0)
	v_mul_f32_e32 v58, v52, v57
	v_fmac_f32_e32 v58, v48, v56
	v_mul_f32_e32 v48, v48, v57
	v_fma_f32 v48, v52, v56, -v48
	global_load_dwordx2 v[56:57], v[74:75], off
	v_bfe_u32 v59, v58, 16, 1
	v_bfe_u32 v52, v48, 16, 1
	v_add3_u32 v58, v58, v59, s70
	v_add_u32_e32 v59, v138, v137
	v_add3_u32 v48, v48, v52, s70
	ds_write_b16_d16_hi v59, v48 offset:55424
	v_mfma_f32_16x16x32_bf16 v[8:11], v[28:31], v[246:249], v[234:237]
	ds_write_b16_d16_hi v59, v58 offset:55296
	s_waitcnt vmcnt(0)
	v_mul_f32_e32 v48, v53, v57
	v_fmac_f32_e32 v48, v49, v56
	v_bfe_u32 v52, v48, 16, 1
	v_add3_u32 v48, v48, v52, s70
	ds_write_b16_d16_hi v59, v48 offset:55584
	v_mul_f32_e32 v48, v49, v57
	v_fma_f32 v48, v53, v56, -v48
	v_bfe_u32 v49, v48, 16, 1
	v_add3_u32 v48, v48, v49, s70
	ds_write_b16_d16_hi v59, v48 offset:55712
	global_load_dwordx2 v[48:49], v[76:77], off
	v_mfma_f32_16x16x32_bf16 v[0:3], v[28:31], v[198:201], v[168:171]
	s_waitcnt vmcnt(0)
	v_mul_f32_e32 v52, v54, v49
	v_mul_f32_e32 v49, v50, v49
	v_fmac_f32_e32 v52, v50, v48
	v_fma_f32 v48, v54, v48, -v49
	v_bfe_u32 v49, v48, 16, 1
	v_add3_u32 v48, v48, v49, s70
	ds_write_b16_d16_hi v59, v48 offset:56000
	global_load_dwordx2 v[48:49], v[78:79], off
	v_bfe_u32 v53, v52, 16, 1
	v_add3_u32 v52, v52, v53, s70
	ds_write_b16_d16_hi v59, v52 offset:55872
	v_mfma_f32_16x16x32_bf16 v[28:31], v[188:191], v[206:209], v[172:175]
	s_waitcnt vmcnt(0)
	v_mul_f32_e32 v50, v55, v49
	v_mul_f32_e32 v49, v51, v49
	v_fmac_f32_e32 v50, v51, v48
	v_fma_f32 v48, v55, v48, -v49
	v_bfe_u32 v49, v48, 16, 1
	v_add3_u32 v48, v48, v49, s70
	ds_write_b16_d16_hi v59, v48 offset:56288
	global_load_dwordx2 v[48:49], v[80:81], off
	v_bfe_u32 v52, v50, 16, 1
	v_add3_u32 v50, v50, v52, s70
	ds_write_b16_d16_hi v59, v50 offset:56160
	v_mfma_f32_16x16x32_bf16 v[20:23], v[188:191], v[242:245], v[20:23]
	s_waitcnt vmcnt(0)
	v_mul_f32_e32 v50, v44, v49
	v_fmac_f32_e32 v50, v40, v48
	v_mul_f32_e32 v40, v40, v49
	v_fma_f32 v40, v44, v48, -v40
	global_load_dwordx2 v[48:49], v[82:83], off
	v_bfe_u32 v51, v50, 16, 1
	v_bfe_u32 v44, v40, 16, 1
	v_add3_u32 v50, v50, v51, s70
	v_add_u32_e32 v51, v139, v137
	v_add3_u32 v40, v40, v44, s70
	ds_write_b16_d16_hi v51, v40 offset:55424
	ds_write_b16_d16_hi v51, v50 offset:55296
	v_mfma_f32_16x16x32_bf16 v[12:15], v[188:191], v[246:249], v[180:183]
	s_waitcnt vmcnt(0)
	v_mul_f32_e32 v40, v45, v49
	v_fmac_f32_e32 v40, v41, v48
	v_bfe_u32 v44, v40, 16, 1
	v_add3_u32 v40, v40, v44, s70
	ds_write_b16_d16_hi v51, v40 offset:55584
	v_mul_f32_e32 v40, v41, v49
	v_fma_f32 v40, v45, v48, -v40
	v_bfe_u32 v41, v40, 16, 1
	v_add3_u32 v40, v40, v41, s70
	ds_write_b16_d16_hi v51, v40 offset:55712
	global_load_dwordx2 v[40:41], v[84:85], off
	v_mfma_f32_16x16x32_bf16 v[4:7], v[188:191], v[198:201], v[176:179]
	s_waitcnt vmcnt(0)
	v_mul_f32_e32 v44, v46, v41
	v_mul_f32_e32 v41, v42, v41
	v_fmac_f32_e32 v44, v42, v40
	v_fma_f32 v40, v46, v40, -v41
	v_bfe_u32 v41, v40, 16, 1
	v_add3_u32 v40, v40, v41, s70
	ds_write_b16_d16_hi v51, v40 offset:56000
	global_load_dwordx2 v[40:41], v[86:87], off
	v_bfe_u32 v45, v44, 16, 1
	v_add3_u32 v44, v44, v45, s70
	ds_write_b16_d16_hi v51, v44 offset:55872
	s_waitcnt vmcnt(0)
	v_mul_f32_e32 v42, v47, v41
	v_mul_f32_e32 v41, v43, v41
	v_fmac_f32_e32 v42, v43, v40
	v_fma_f32 v40, v47, v40, -v41
	v_bfe_u32 v41, v40, 16, 1
	v_add3_u32 v40, v40, v41, s70
	ds_write_b16_d16_hi v51, v40 offset:56288
	global_load_dwordx2 v[40:41], v[88:89], off
	v_bfe_u32 v44, v42, 16, 1
	v_add3_u32 v42, v42, v44, s70
	ds_write_b16_d16_hi v51, v42 offset:56160
	s_waitcnt vmcnt(0)
	v_mul_f32_e32 v42, v36, v41
	v_fmac_f32_e32 v42, v32, v40
	v_mul_f32_e32 v32, v32, v41
	v_fma_f32 v32, v36, v40, -v32
	global_load_dwordx2 v[40:41], v[90:91], off
	v_bfe_u32 v43, v42, 16, 1
	v_bfe_u32 v36, v32, 16, 1
	v_add3_u32 v42, v42, v43, s70
	v_add_u32_e32 v43, v140, v137
	v_add3_u32 v32, v32, v36, s70
	ds_write_b16_d16_hi v43, v32 offset:55424
	ds_write_b16_d16_hi v43, v42 offset:55296
	s_waitcnt vmcnt(0)
	v_mul_f32_e32 v32, v37, v41
	v_fmac_f32_e32 v32, v33, v40
	v_bfe_u32 v36, v32, 16, 1
	v_add3_u32 v32, v32, v36, s70
	ds_write_b16_d16_hi v43, v32 offset:55584
	v_mul_f32_e32 v32, v33, v41
	v_fma_f32 v32, v37, v40, -v32
	v_bfe_u32 v33, v32, 16, 1
	v_add3_u32 v32, v32, v33, s70
	ds_write_b16_d16_hi v43, v32 offset:55712
	global_load_dwordx2 v[32:33], v[92:93], off
	s_waitcnt vmcnt(0)
	v_mul_f32_e32 v36, v38, v33
	v_mul_f32_e32 v33, v34, v33
	v_fmac_f32_e32 v36, v34, v32
	v_fma_f32 v32, v38, v32, -v33
	v_bfe_u32 v33, v32, 16, 1
	v_add3_u32 v32, v32, v33, s70
	ds_write_b16_d16_hi v43, v32 offset:56000
	global_load_dwordx2 v[32:33], v[94:95], off
	v_bfe_u32 v37, v36, 16, 1
	v_add3_u32 v36, v36, v37, s70
	ds_write_b16_d16_hi v43, v36 offset:55872
	s_waitcnt vmcnt(0)
	v_mul_f32_e32 v34, v39, v33
	v_mul_f32_e32 v33, v35, v33
	v_fmac_f32_e32 v34, v35, v32
	v_fma_f32 v32, v39, v32, -v33
	v_bfe_u32 v33, v32, 16, 1
	v_add3_u32 v32, v32, v33, s70
	ds_write_b16_d16_hi v43, v32 offset:56288
	global_load_dwordx2 v[32:33], v[96:97], off
	v_bfe_u32 v36, v34, 16, 1
	v_add3_u32 v34, v34, v36, s70
	ds_write_b16_d16_hi v43, v34 offset:56160
	s_waitcnt vmcnt(0)
	v_mul_f32_e32 v34, v28, v33
	v_fmac_f32_e32 v34, v24, v32
	v_mul_f32_e32 v24, v24, v33
	v_fma_f32 v24, v28, v32, -v24
	global_load_dwordx2 v[32:33], v[98:99], off
	v_bfe_u32 v35, v34, 16, 1
	v_bfe_u32 v28, v24, 16, 1
	v_add3_u32 v34, v34, v35, s70
	v_add_u32_e32 v35, v136, v141
	v_add3_u32 v24, v24, v28, s70
	ds_write_b16_d16_hi v35, v24 offset:55424
	ds_write_b16_d16_hi v35, v34 offset:55296
	s_waitcnt vmcnt(0)
	v_mul_f32_e32 v24, v29, v33
	v_fmac_f32_e32 v24, v25, v32
	v_bfe_u32 v28, v24, 16, 1
	v_add3_u32 v24, v24, v28, s70
	ds_write_b16_d16_hi v35, v24 offset:55584
	v_mul_f32_e32 v24, v25, v33
	v_fma_f32 v24, v29, v32, -v24
	v_bfe_u32 v25, v24, 16, 1
	v_add3_u32 v24, v24, v25, s70
	ds_write_b16_d16_hi v35, v24 offset:55712
	global_load_dwordx2 v[24:25], v[100:101], off
	s_waitcnt vmcnt(0)
	v_mul_f32_e32 v28, v30, v25
	v_mul_f32_e32 v25, v26, v25
	v_fmac_f32_e32 v28, v26, v24
	v_fma_f32 v24, v30, v24, -v25
	v_bfe_u32 v25, v24, 16, 1
	v_add3_u32 v24, v24, v25, s70
	ds_write_b16_d16_hi v35, v24 offset:56000
	global_load_dwordx2 v[24:25], v[102:103], off
	v_bfe_u32 v29, v28, 16, 1
	v_add3_u32 v28, v28, v29, s70
	ds_write_b16_d16_hi v35, v28 offset:55872
	s_waitcnt vmcnt(0)
	v_mul_f32_e32 v26, v31, v25
	v_mul_f32_e32 v25, v27, v25
	v_fmac_f32_e32 v26, v27, v24
	v_fma_f32 v24, v31, v24, -v25
	v_bfe_u32 v25, v24, 16, 1
	v_add3_u32 v24, v24, v25, s70
	ds_write_b16_d16_hi v35, v24 offset:56288
	global_load_dwordx2 v[24:25], v[104:105], off
	v_bfe_u32 v28, v26, 16, 1
	v_add3_u32 v26, v26, v28, s70
	ds_write_b16_d16_hi v35, v26 offset:56160
	s_waitcnt vmcnt(0)
	v_mul_f32_e32 v26, v20, v25
	v_fmac_f32_e32 v26, v16, v24
	v_mul_f32_e32 v16, v16, v25
	v_fma_f32 v16, v20, v24, -v16
	global_load_dwordx2 v[24:25], v[106:107], off
	v_bfe_u32 v27, v26, 16, 1
	v_bfe_u32 v20, v16, 16, 1
	v_add3_u32 v26, v26, v27, s70
	v_add_u32_e32 v27, v138, v141
	v_add3_u32 v16, v16, v20, s70
	ds_write_b16_d16_hi v27, v16 offset:55424
	ds_write_b16_d16_hi v27, v26 offset:55296
	s_waitcnt vmcnt(0)
	v_mul_f32_e32 v16, v21, v25
	v_fmac_f32_e32 v16, v17, v24
	v_bfe_u32 v20, v16, 16, 1
	v_add3_u32 v16, v16, v20, s70
	ds_write_b16_d16_hi v27, v16 offset:55584
	v_mul_f32_e32 v16, v17, v25
	v_fma_f32 v16, v21, v24, -v16
	v_bfe_u32 v17, v16, 16, 1
	v_add3_u32 v16, v16, v17, s70
	ds_write_b16_d16_hi v27, v16 offset:55712
	global_load_dwordx2 v[16:17], v[108:109], off
	s_waitcnt vmcnt(0)
	v_mul_f32_e32 v20, v22, v17
	v_mul_f32_e32 v17, v18, v17
	v_fmac_f32_e32 v20, v18, v16
	v_fma_f32 v16, v22, v16, -v17
	v_bfe_u32 v17, v16, 16, 1
	v_add3_u32 v16, v16, v17, s70
	ds_write_b16_d16_hi v27, v16 offset:56000
	global_load_dwordx2 v[16:17], v[110:111], off
	v_bfe_u32 v21, v20, 16, 1
	v_add3_u32 v20, v20, v21, s70
	ds_write_b16_d16_hi v27, v20 offset:55872
	s_waitcnt vmcnt(0)
	v_mul_f32_e32 v18, v23, v17
	v_mul_f32_e32 v17, v19, v17
	v_fmac_f32_e32 v18, v19, v16
	v_fma_f32 v16, v23, v16, -v17
	v_bfe_u32 v17, v16, 16, 1
	v_add3_u32 v16, v16, v17, s70
	ds_write_b16_d16_hi v27, v16 offset:56288
	global_load_dwordx2 v[16:17], v[114:115], off
	v_bfe_u32 v20, v18, 16, 1
	v_add3_u32 v18, v18, v20, s70
	ds_write_b16_d16_hi v27, v18 offset:56160
	s_waitcnt vmcnt(0)
	v_mul_f32_e32 v18, v12, v17
	v_fmac_f32_e32 v18, v8, v16
	v_mul_f32_e32 v8, v8, v17
	v_fma_f32 v8, v12, v16, -v8
	global_load_dwordx2 v[16:17], v[116:117], off
	v_bfe_u32 v19, v18, 16, 1
	v_bfe_u32 v12, v8, 16, 1
	v_add3_u32 v18, v18, v19, s70
	v_add_u32_e32 v19, v139, v141
	v_add3_u32 v8, v8, v12, s70
	ds_write_b16_d16_hi v19, v8 offset:55424
	ds_write_b16_d16_hi v19, v18 offset:55296
	s_waitcnt vmcnt(0)
	v_mul_f32_e32 v8, v13, v17
	v_fmac_f32_e32 v8, v9, v16
	v_bfe_u32 v12, v8, 16, 1
	v_add3_u32 v8, v8, v12, s70
	ds_write_b16_d16_hi v19, v8 offset:55584
	v_mul_f32_e32 v8, v9, v17
	v_fma_f32 v8, v13, v16, -v8
	v_bfe_u32 v9, v8, 16, 1
	v_add3_u32 v8, v8, v9, s70
	ds_write_b16_d16_hi v19, v8 offset:55712
	global_load_dwordx2 v[8:9], v[118:119], off
	s_waitcnt vmcnt(0)
	v_mul_f32_e32 v12, v14, v9
	v_mul_f32_e32 v9, v10, v9
	v_fmac_f32_e32 v12, v10, v8
	v_fma_f32 v8, v14, v8, -v9
	v_bfe_u32 v9, v8, 16, 1
	v_add3_u32 v8, v8, v9, s70
	ds_write_b16_d16_hi v19, v8 offset:56000
	global_load_dwordx2 v[8:9], v[120:121], off
	v_bfe_u32 v13, v12, 16, 1
	v_add3_u32 v12, v12, v13, s70
	ds_write_b16_d16_hi v19, v12 offset:55872
	s_waitcnt vmcnt(0)
	v_mul_f32_e32 v10, v15, v9
	v_mul_f32_e32 v9, v11, v9
	v_fmac_f32_e32 v10, v11, v8
	v_fma_f32 v8, v15, v8, -v9
	v_bfe_u32 v9, v8, 16, 1
	v_add3_u32 v8, v8, v9, s70
	ds_write_b16_d16_hi v19, v8 offset:56288
	global_load_dwordx2 v[8:9], v[122:123], off
	v_bfe_u32 v12, v10, 16, 1
	v_add3_u32 v10, v10, v12, s70
	ds_write_b16_d16_hi v19, v10 offset:56160
	s_waitcnt vmcnt(0)
	v_mul_f32_e32 v10, v4, v9
	v_fmac_f32_e32 v10, v0, v8
	v_mul_f32_e32 v0, v0, v9
	v_fma_f32 v0, v4, v8, -v0
	global_load_dwordx2 v[8:9], v[124:125], off
	v_bfe_u32 v11, v10, 16, 1
	v_bfe_u32 v4, v0, 16, 1
	v_add3_u32 v10, v10, v11, s70
	v_add_u32_e32 v11, v140, v141
	v_add3_u32 v0, v0, v4, s70
	ds_write_b16_d16_hi v11, v0 offset:55424
	ds_write_b16_d16_hi v11, v10 offset:55296
	s_waitcnt vmcnt(0)
	v_mul_f32_e32 v0, v5, v9
	v_fmac_f32_e32 v0, v1, v8
	v_bfe_u32 v4, v0, 16, 1
	v_add3_u32 v0, v0, v4, s70
	ds_write_b16_d16_hi v11, v0 offset:55584
	v_mul_f32_e32 v0, v1, v9
	v_fma_f32 v0, v5, v8, -v0
	v_bfe_u32 v1, v0, 16, 1
	v_add3_u32 v0, v0, v1, s70
	ds_write_b16_d16_hi v11, v0 offset:55712
	global_load_dwordx2 v[0:1], v[126:127], off
	v_add_u32_e32 v8, v133, v134
	v_add_u32_e32 v9, v132, v135
	s_waitcnt vmcnt(0)
	v_mul_f32_e32 v4, v6, v1
	v_mul_f32_e32 v1, v2, v1
	v_fmac_f32_e32 v4, v2, v0
	v_fma_f32 v0, v6, v0, -v1
	v_bfe_u32 v1, v0, 16, 1
	v_add3_u32 v0, v0, v1, s70
	ds_write_b16_d16_hi v11, v0 offset:56000
	global_load_dwordx2 v[0:1], v[128:129], off
	v_bfe_u32 v5, v4, 16, 1
	v_add3_u32 v4, v4, v5, s70
	ds_write_b16_d16_hi v11, v4 offset:55872
	s_waitcnt vmcnt(0)
	v_mul_f32_e32 v2, v7, v1
	v_mul_f32_e32 v1, v3, v1
	v_fmac_f32_e32 v2, v3, v0
	v_fma_f32 v0, v7, v0, -v1
	v_bfe_u32 v4, v2, 16, 1
	v_bfe_u32 v1, v0, 16, 1
	v_add3_u32 v2, v2, v4, s70
	v_add3_u32 v0, v0, v1, s70
	ds_write_b16_d16_hi v11, v2 offset:56160
	ds_write_b16_d16_hi v11, v0 offset:56288
	s_waitcnt lgkmcnt(0)
	s_barrier
	ds_read_b128 v[4:7], v8 offset:55296
	ds_read_b128 v[0:3], v8 offset:59904
	ds_read_b128 v[10:13], v9 offset:36864
	ds_read_b128 v[14:17], v9 offset:41472
	ds_read_b128 v[18:21], v9 offset:46080
	ds_read_b128 v[22:25], v9 offset:50688
	s_waitcnt lgkmcnt(3)
	v_mfma_f32_16x16x32_bf16 v[26:29], v[4:7], v[10:13], 0
	s_waitcnt lgkmcnt(2)
	v_mfma_f32_16x16x32_bf16 v[30:33], v[4:7], v[14:17], 0
	s_waitcnt lgkmcnt(1)
	v_mfma_f32_16x16x32_bf16 v[34:37], v[4:7], v[18:21], 0
	s_waitcnt lgkmcnt(0)
	v_mfma_f32_16x16x32_bf16 v[4:7], v[4:7], v[22:25], 0
	v_mfma_f32_16x16x32_bf16 v[10:13], v[0:3], v[10:13], 0
	v_mfma_f32_16x16x32_bf16 v[14:17], v[0:3], v[14:17], 0
	v_mfma_f32_16x16x32_bf16 v[18:21], v[0:3], v[18:21], 0
	v_mfma_f32_16x16x32_bf16 v[0:3], v[0:3], v[22:25], 0
	ds_read_b128 v[22:25], v8 offset:55360
	ds_read_b128 v[38:41], v8 offset:59968
	ds_read_b128 v[42:45], v9 offset:36928
	ds_read_b128 v[46:49], v9 offset:41536
	ds_read_b128 v[50:53], v9 offset:46144
	ds_read_b128 v[54:57], v9 offset:50752
	s_waitcnt lgkmcnt(3)
	v_mfma_f32_16x16x32_bf16 v[26:29], v[22:25], v[42:45], v[26:29]
	s_waitcnt lgkmcnt(2)
	v_mfma_f32_16x16x32_bf16 v[30:33], v[22:25], v[46:49], v[30:33]
	s_waitcnt lgkmcnt(1)
	v_mfma_f32_16x16x32_bf16 v[34:37], v[22:25], v[50:53], v[34:37]
	s_waitcnt lgkmcnt(0)
	v_mfma_f32_16x16x32_bf16 v[4:7], v[22:25], v[54:57], v[4:7]
	v_mfma_f32_16x16x32_bf16 v[10:13], v[38:41], v[42:45], v[10:13]
	v_mfma_f32_16x16x32_bf16 v[14:17], v[38:41], v[46:49], v[14:17]
	v_mfma_f32_16x16x32_bf16 v[18:21], v[38:41], v[50:53], v[18:21]
	v_mfma_f32_16x16x32_bf16 v[0:3], v[38:41], v[54:57], v[0:3]
	ds_read_b128 v[22:25], v8 offset:55424
	ds_read_b128 v[38:41], v8 offset:60032
	ds_read_b128 v[42:45], v9 offset:36992
	ds_read_b128 v[46:49], v9 offset:41600
	ds_read_b128 v[50:53], v9 offset:46208
	ds_read_b128 v[54:57], v9 offset:50816
	s_waitcnt lgkmcnt(3)
	v_mfma_f32_16x16x32_bf16 v[26:29], v[22:25], v[42:45], v[26:29]
	s_waitcnt lgkmcnt(2)
	v_mfma_f32_16x16x32_bf16 v[30:33], v[22:25], v[46:49], v[30:33]
	s_waitcnt lgkmcnt(1)
	v_mfma_f32_16x16x32_bf16 v[34:37], v[22:25], v[50:53], v[34:37]
	s_waitcnt lgkmcnt(0)
	v_mfma_f32_16x16x32_bf16 v[4:7], v[22:25], v[54:57], v[4:7]
	v_mfma_f32_16x16x32_bf16 v[10:13], v[38:41], v[42:45], v[10:13]
	v_mfma_f32_16x16x32_bf16 v[14:17], v[38:41], v[46:49], v[14:17]
	v_mfma_f32_16x16x32_bf16 v[18:21], v[38:41], v[50:53], v[18:21]
	v_mfma_f32_16x16x32_bf16 v[0:3], v[38:41], v[54:57], v[0:3]
	ds_read_b128 v[22:25], v8 offset:55488
	ds_read_b128 v[38:41], v8 offset:60096
	ds_read_b128 v[42:45], v9 offset:37056
	ds_read_b128 v[46:49], v9 offset:41664
	ds_read_b128 v[50:53], v9 offset:46272
	ds_read_b128 v[54:57], v9 offset:50880
	s_waitcnt lgkmcnt(0)
	s_barrier
	v_mfma_f32_16x16x32_bf16 v[26:29], v[22:25], v[42:45], v[26:29]
	v_mfma_f32_16x16x32_bf16 v[8:11], v[38:41], v[42:45], v[10:13]
	v_mfma_f32_16x16x32_bf16 v[12:15], v[38:41], v[46:49], v[14:17]
	v_mfma_f32_16x16x32_bf16 v[16:19], v[38:41], v[50:53], v[18:21]
	s_nop 4
	v_bfe_u32 v20, v26, 16, 1
	v_add3_u32 v20, v26, v20, s70
	ds_write_b16_d16_hi v142, v20 offset:55296
	v_bfe_u32 v20, v27, 16, 1
	v_add3_u32 v20, v27, v20, s70
	v_mfma_f32_16x16x32_bf16 v[30:33], v[22:25], v[46:49], v[30:33]
	ds_write_b16_d16_hi v142, v20 offset:55304
	v_bfe_u32 v20, v28, 16, 1
	v_add3_u32 v20, v28, v20, s70
	ds_write_b16_d16_hi v142, v20 offset:55312
	v_bfe_u32 v20, v29, 16, 1
	v_add3_u32 v20, v29, v20, s70
	ds_write_b16_d16_hi v142, v20 offset:55320
	s_nop 0
	v_bfe_u32 v20, v30, 16, 1
	v_add3_u32 v20, v30, v20, s70
	ds_write_b16_d16_hi v142, v20 offset:63488
	v_bfe_u32 v20, v31, 16, 1
	v_add3_u32 v20, v31, v20, s70
	v_mfma_f32_16x16x32_bf16 v[34:37], v[22:25], v[50:53], v[34:37]
	ds_write_b16_d16_hi v142, v20 offset:63496
	v_bfe_u32 v20, v32, 16, 1
	v_add3_u32 v20, v32, v20, s70
	ds_write_b16_d16_hi v142, v20 offset:63504
	v_bfe_u32 v20, v33, 16, 1
	v_add3_u32 v20, v33, v20, s70
	ds_write_b16_d16_hi v142, v20 offset:63512
	s_nop 0
	v_bfe_u32 v20, v34, 16, 1
	v_add3_u32 v20, v34, v20, s70
	ds_write_b16_d16_hi v143, v20 offset:16384
	v_bfe_u32 v20, v35, 16, 1
	v_add3_u32 v20, v35, v20, s70
	v_mfma_f32_16x16x32_bf16 v[4:7], v[22:25], v[54:57], v[4:7]
	ds_write_b16_d16_hi v143, v20 offset:16392
	v_bfe_u32 v20, v36, 16, 1
	v_add3_u32 v20, v36, v20, s70
	ds_write_b16_d16_hi v143, v20 offset:16400
	v_bfe_u32 v20, v37, 16, 1
	v_add3_u32 v20, v37, v20, s70
	ds_write_b16_d16_hi v143, v20 offset:16408
	s_nop 0
	v_bfe_u32 v20, v4, 16, 1
	v_add3_u32 v4, v4, v20, s70
	ds_write_b16_d16_hi v143, v4 offset:24576
	v_bfe_u32 v4, v5, 16, 1
	v_add3_u32 v4, v5, v4, s70
	ds_write_b16_d16_hi v143, v4 offset:24584
	v_bfe_u32 v4, v6, 16, 1
	v_add3_u32 v4, v6, v4, s70
	ds_write_b16_d16_hi v143, v4 offset:24592
	v_bfe_u32 v4, v7, 16, 1
	v_add3_u32 v4, v7, v4, s70
	ds_write_b16_d16_hi v143, v4 offset:24600
	v_bfe_u32 v4, v8, 16, 1
	v_add3_u32 v4, v8, v4, s70
	ds_write_b16_d16_hi v142, v4 offset:55424
	v_bfe_u32 v4, v9, 16, 1
	v_add3_u32 v4, v9, v4, s70
	ds_write_b16_d16_hi v142, v4 offset:55432
	v_bfe_u32 v4, v10, 16, 1
	v_add3_u32 v4, v10, v4, s70
	ds_write_b16_d16_hi v142, v4 offset:55440
	v_bfe_u32 v4, v11, 16, 1
	v_add3_u32 v4, v11, v4, s70
	ds_write_b16_d16_hi v142, v4 offset:55448
	v_bfe_u32 v4, v12, 16, 1
	v_add3_u32 v4, v12, v4, s70
	ds_write_b16_d16_hi v142, v4 offset:63616
	v_bfe_u32 v4, v13, 16, 1
	v_add3_u32 v4, v13, v4, s70
	ds_write_b16_d16_hi v142, v4 offset:63624
	v_bfe_u32 v4, v14, 16, 1
	v_add3_u32 v4, v14, v4, s70
	ds_write_b16_d16_hi v142, v4 offset:63632
	v_bfe_u32 v4, v15, 16, 1
	v_add3_u32 v4, v15, v4, s70
	ds_write_b16_d16_hi v142, v4 offset:63640
	v_bfe_u32 v4, v16, 16, 1
	v_add3_u32 v4, v16, v4, s70
	ds_write_b16_d16_hi v143, v4 offset:16512
	v_bfe_u32 v4, v17, 16, 1
	v_add3_u32 v4, v17, v4, s70
	v_mfma_f32_16x16x32_bf16 v[0:3], v[38:41], v[54:57], v[0:3]
	ds_write_b16_d16_hi v143, v4 offset:16520
	v_bfe_u32 v4, v18, 16, 1
	v_add3_u32 v4, v18, v4, s70
	ds_write_b16_d16_hi v143, v4 offset:16528
	v_bfe_u32 v4, v19, 16, 1
	v_add3_u32 v4, v19, v4, s70
	ds_write_b16_d16_hi v143, v4 offset:16536
	s_nop 0
	v_bfe_u32 v4, v0, 16, 1
	v_add3_u32 v0, v0, v4, s70
	ds_write_b16_d16_hi v143, v0 offset:24704
	v_bfe_u32 v0, v1, 16, 1
	v_add3_u32 v0, v1, v0, s70
	ds_write_b16_d16_hi v143, v0 offset:24712
	v_bfe_u32 v0, v2, 16, 1
	v_add3_u32 v0, v2, v0, s70
	ds_write_b16_d16_hi v143, v0 offset:24720
	v_bfe_u32 v0, v3, 16, 1
	v_add3_u32 v0, v3, v0, s70
	ds_write_b16_d16_hi v143, v0 offset:24728
	s_waitcnt lgkmcnt(0)
	s_barrier
	ds_read_b64 v[0:1], v152 offset:55296
	v_add_u32_e32 v2, s1, v130
	v_ashrrev_i32_e32 v3, 31, v2
	v_lshlrev_b64 v[2:3], 12, v[2:3]
	v_lshl_add_u64 v[2:3], s[16:17], 0, v[2:3]
	s_waitcnt lgkmcnt(0)
	global_store_dwordx2 v[2:3], v[0:1], off
	ds_read_b64 v[0:1], v153 offset:55296
	v_add_u32_e32 v2, s1, v144
	v_ashrrev_i32_e32 v3, 31, v2
	v_lshlrev_b64 v[2:3], 12, v[2:3]
	v_lshl_add_u64 v[2:3], s[16:17], 0, v[2:3]
	s_waitcnt lgkmcnt(0)
	global_store_dwordx2 v[2:3], v[0:1], off
	ds_read_b64 v[0:1], v154 offset:55296
	v_add_u32_e32 v2, s1, v145
	v_ashrrev_i32_e32 v3, 31, v2
	v_lshlrev_b64 v[2:3], 12, v[2:3]
	v_lshl_add_u64 v[2:3], s[16:17], 0, v[2:3]
	s_waitcnt lgkmcnt(0)
	global_store_dwordx2 v[2:3], v[0:1], off
	ds_read_b64 v[0:1], v155 offset:55296
	v_add_u32_e32 v2, s1, v146
	v_ashrrev_i32_e32 v3, 31, v2
	v_lshlrev_b64 v[2:3], 12, v[2:3]
	v_lshl_add_u64 v[2:3], s[16:17], 0, v[2:3]
	s_waitcnt lgkmcnt(0)
	global_store_dwordx2 v[2:3], v[0:1], off
	ds_read_b64 v[0:1], v156 offset:55296
	v_add_u32_e32 v2, s1, v147
	v_ashrrev_i32_e32 v3, 31, v2
	v_lshlrev_b64 v[2:3], 12, v[2:3]
	v_lshl_add_u64 v[2:3], s[16:17], 0, v[2:3]
	s_waitcnt lgkmcnt(0)
	global_store_dwordx2 v[2:3], v[0:1], off
	ds_read_b64 v[0:1], v157 offset:55296
	v_add_u32_e32 v2, s1, v148
	v_ashrrev_i32_e32 v3, 31, v2
	v_lshlrev_b64 v[2:3], 12, v[2:3]
	v_lshl_add_u64 v[2:3], s[16:17], 0, v[2:3]
	s_waitcnt lgkmcnt(0)
	global_store_dwordx2 v[2:3], v[0:1], off
	ds_read_b64 v[0:1], v158 offset:55296
	v_add_u32_e32 v2, s1, v149
	v_ashrrev_i32_e32 v3, 31, v2
	v_lshlrev_b64 v[2:3], 12, v[2:3]
	v_lshl_add_u64 v[2:3], s[16:17], 0, v[2:3]
	s_waitcnt lgkmcnt(0)
	global_store_dwordx2 v[2:3], v[0:1], off
	ds_read_b64 v[0:1], v159 offset:55296
	v_add_u32_e32 v2, s1, v150
	v_ashrrev_i32_e32 v3, 31, v2
	v_lshlrev_b64 v[2:3], 12, v[2:3]
	v_lshl_add_u64 v[2:3], s[16:17], 0, v[2:3]
	s_waitcnt lgkmcnt(0)
	global_store_dwordx2 v[2:3], v[0:1], off
	s_cbranch_scc1 .LBB1_480
	s_movk_i32 s25, 0x120
